# diff tile-load addresses: constants added on the scalar unit, one 64-bit VALU add per address
# speedup vs baseline: 1.0217x; 1.0048x over previous
; #define D_LOAD(key0) do { st0 = *(const u32x4*)(kg + (size_t)(key0) * 1024); st1 = *(const u32x4*)(kg + (size_t)((key0) + 32) * 1024); st2 = *(const u32x4*)(vg + (size_t)(key0) * 1024); st3 = *(const u32x4*)(vg + (size_t)((key0) + 32) * 1024); } while (0)
; #define D_STORE(buf) do { *(LAS u32x4*)(lds + klds + (buf) * DK_BUF) = st0; *(LAS u32x4*)(lds + klds + (buf) * DK_BUF + 32 * DK_STR) = st1; *(LAS u32x4*)(lds + vlds + (buf) * DV_BUF) = st2; *(LAS u32x4*)(lds + vlds + (buf) * DV_BUF + 32 * DV_STR) = st3; } while (0)
; __device__ __forceinline__ void diff_unit(const Frame& F, int b, int h, int qi, float lam, int dry) {
;     ...
;     const int nt = 2 * qi + 3;
;     __syncthreads();
;     D_LOAD(0); D_STORE(0);
;     __syncthreads();
;     f32x16 O[4];
; #pragma unroll
;     for (int dt = 0; dt < 4; ++dt)
; #pragma unroll
;         for (int r = 0; r < 16; ++r) O[dt][r] = 0.f;
;     float ms = -INFINITY, lsum = 0.f;
;     const int kra = D_KOFF + r32 * DK_STR + map * 128 + hi * 16;
;     const int vra = D_VOFF + (4 * hi + ((lane & 15) >> 2)) * DV_STR + (16 * ((lane >> 4) & 1) + 4 * (lane & 3)) * 2;
;     for (int it = 0; it < nt; ++it) {
;         const int key0 = it == 0 ? 0 : NMETA + 64 * (it - 1);
;         if (it + 1 < nt) D_LOAD(NMETA + 64 * it);
.LBB0_300:
	s_add_u32 s0, s64, 0x6d28000
	s_addc_u32 s1, s65, 0
	v_lshl_add_u64 v[66:67], v[186:187], 0, s[0:1]
	s_add_u32 s0, s64, 0x6d38000
	s_addc_u32 s1, s65, 0
	v_lshl_add_u64 v[68:69], v[186:187], 0, s[0:1]
	s_add_u32 s0, s64, 0xae28000
	s_addc_u32 s1, s65, 0
	v_lshl_add_u64 v[64:65], v[186:187], 0, s[0:1]
	s_add_u32 s0, s64, 0xae38000
	s_addc_u32 s1, s65, 0
	v_lshl_add_u64 v[70:71], v[186:187], 0, s[0:1]
	global_load_dwordx4 v[112:115], v[66:67], off
	global_load_dwordx4 v[116:119], v[68:69], off
	global_load_dwordx4 v[120:123], v[64:65], off
	global_load_dwordx4 v[124:127], v[70:71], off
	s_cmp_gt_u32 s91, s70
	s_cbranch_scc1 .LBB0_299

; #define D_LOAD(key0) do { st0 = *(const u32x4*)(kg + (size_t)(key0) * 1024); st1 = *(const u32x4*)(kg + (size_t)((key0) + 32) * 1024); st2 = *(const u32x4*)(vg + (size_t)(key0) * 1024); st3 = *(const u32x4*)(vg + (size_t)((key0) + 32) * 1024); } while (0)
; #define D_STORE(buf) do { *(LAS u32x4*)(lds + klds + (buf) * DK_BUF) = st0; *(LAS u32x4*)(lds + klds + (buf) * DK_BUF + 32 * DK_STR) = st1; *(LAS u32x4*)(lds + vlds + (buf) * DV_BUF) = st2; *(LAS u32x4*)(lds + vlds + (buf) * DV_BUF + 32 * DV_STR) = st3; } while (0)
; __device__ __forceinline__ void diff_unit(const Frame& F, int b, int h, int qi, float lam, int dry) {
;     ...
;     const int nt = 2 * qi + 3;
;     __syncthreads();
;     D_LOAD(0); D_STORE(0);
;     __syncthreads();
;     f32x16 O[4];
; #pragma unroll
;     for (int dt = 0; dt < 4; ++dt)
; #pragma unroll
;         for (int r = 0; r < 16; ++r) O[dt][r] = 0.f;
;     float ms = -INFINITY, lsum = 0.f;
;     const int kra = D_KOFF + r32 * DK_STR + map * 128 + hi * 16;
;     const int vra = D_VOFF + (4 * hi + ((lane & 15) >> 2)) * DV_STR + (16 * ((lane >> 4) & 1) + 4 * (lane & 3)) * 2;
;     for (int it = 0; it < nt; ++it) {
;         const int key0 = it == 0 ? 0 : NMETA + 64 * (it - 1);
;         if (it + 1 < nt) D_LOAD(NMETA + 64 * it);
.LBB0_319:
	s_add_u32 s0, s66, 0x6d28000
	s_addc_u32 s1, s67, 0
	v_lshl_add_u64 v[66:67], v[186:187], 0, s[0:1]
	s_add_u32 s0, s66, 0x6d38000
	s_addc_u32 s1, s67, 0
	v_lshl_add_u64 v[68:69], v[186:187], 0, s[0:1]
	s_add_u32 s0, s66, 0xae28000
	s_addc_u32 s1, s67, 0
	v_lshl_add_u64 v[64:65], v[186:187], 0, s[0:1]
	s_add_u32 s0, s66, 0xae38000
	s_addc_u32 s1, s67, 0
	v_lshl_add_u64 v[70:71], v[186:187], 0, s[0:1]
	global_load_dwordx4 v[112:115], v[66:67], off
	global_load_dwordx4 v[116:119], v[68:69], off
	global_load_dwordx4 v[120:123], v[64:65], off
	global_load_dwordx4 v[124:127], v[70:71], off
	s_cmp_gt_u32 s3, s71
	s_cbranch_scc1 .LBB0_318
